# mLSTM combo: VTW hoist + Qs dedupe + counted vmcnt(1) on top of LDS-DMA staging
# baseline (speedup 1.0000x reference)
; #define LAS __attribute__((address_space(3)))
; #define MFMA16(a, b, c) __builtin_amdgcn_mfma_f32_16x16x32_bf16((a), (b), (c), 0, 0, 0)
; __device__ __forceinline__ void mlstm_item(const Args& a, LAS unsigned char* L, bool sample, int b, int hh, int sl, bool dry = false) {
;     ...
;         {
;             typedef short v4i16_t __attribute__((ext_vector_type(4)));
;             v4i16_t tl[2], th[2]; bf16x8 Bv[5];
; #pragma unroll
;             for (int kti = 0; kti < 2; ++kti) { const int kt = 2 * wave + kti;
;                 tl[kti] = __builtin_amdgcn_ds_read_tr16_b64_v4i16((LAS v4i16_t*)(L + L_KS + (g * 8 + (lr >> 2)) * 528 + (kt * 16 + 4 * (lr & 3)) * 2));
;                 th[kti] = __builtin_amdgcn_ds_read_tr16_b64_v4i16((LAS v4i16_t*)(L + L_KS + (g * 8 + 4 + (lr >> 2)) * 528 + (kt * 16 + 4 * (lr & 3)) * 2)); }
; #pragma unroll
;             for (int vt = 0; vt < 5; ++vt) Bv[vt] = *(const LAS bf16x8*)(L + L_VTW + (vt * 16 + lr) * 80 + g * 16);
; #pragma unroll
;             for (int kti = 0; kti < 2; ++kti) { const bf16x8 A = (bf16x8){tl[kti][0], tl[kti][1], tl[kti][2], tl[kti][3], th[kti][0], th[kti][1], th[kti][2], th[kti][3]};
; #pragma unroll
;                 for (int vt = 0; vt < 5; ++vt) Cacc[kti][vt] = MFMA16(A, Bv[vt], Cacc[kti][vt] * dL); }
;         }
.Lhq_skip:
	ds_read_b64_tr_b16 v[58:59], v97 offset:19008
	s_waitcnt lgkmcnt(1)
	ds_read_b64_tr_b16 v[56:57], v97 offset:16896
	ds_read_b64_tr_b16 v[116:117], v97 offset:16912
	ds_read_b64_tr_b16 v[118:119], v97 offset:19024
	v_pk_mul_f32 v[38:39], v[38:39], v[76:77] op_sel_hi:[1,0]
	v_pk_mul_f32 v[36:37], v[36:37], v[76:77] op_sel_hi:[1,0]
	v_pk_mul_f32 v[54:55], v[54:55], v[76:77] op_sel_hi:[1,0]
	v_pk_mul_f32 v[52:53], v[52:53], v[76:77] op_sel_hi:[1,0]
	v_pk_mul_f32 v[50:51], v[50:51], v[76:77] op_sel_hi:[1,0]
	v_pk_mul_f32 v[48:49], v[48:49], v[76:77] op_sel_hi:[1,0]
	v_pk_mul_f32 v[46:47], v[46:47], v[76:77] op_sel_hi:[1,0]
	v_pk_mul_f32 v[44:45], v[44:45], v[76:77] op_sel_hi:[1,0]
	v_pk_mul_f32 v[42:43], v[42:43], v[76:77] op_sel_hi:[1,0]
	v_pk_mul_f32 v[40:41], v[40:41], v[76:77] op_sel_hi:[1,0]
	s_waitcnt lgkmcnt(2)
	v_mfma_f32_16x16x32_bf16 v[36:39], v[56:59], v[4:7], v[36:39]
	v_mul_f32_e64 v34, v34, v76
	v_mul_f32_e64 v35, v35, v76
	v_pk_mul_f32 v[32:33], v[32:33], v[76:77] op_sel_hi:[1,0]
	v_pk_mul_f32 v[30:31], v[30:31], v[76:77] op_sel_hi:[1,0]
	s_waitcnt lgkmcnt(2)
	v_mfma_f32_16x16x32_bf16 v[52:55], v[56:59], v[8:11], v[52:55]
	v_mul_f32_e64 v28, v28, v76
	v_mul_f32_e64 v29, v29, v76
	v_pk_mul_f32 v[26:27], v[26:27], v[76:77] op_sel_hi:[1,0]
	v_pk_mul_f32 v[24:25], v[24:25], v[76:77] op_sel_hi:[1,0]
	s_waitcnt lgkmcnt(2)
	v_mfma_f32_16x16x32_bf16 v[48:51], v[56:59], v[12:15], v[48:51]
	v_mul_f32_e64 v22, v22, v76
	v_mul_f32_e64 v23, v23, v76
	v_pk_mul_f32 v[20:21], v[20:21], v[76:77] op_sel_hi:[1,0]
	v_pk_mul_f32 v[18:19], v[18:19], v[76:77] op_sel_hi:[1,0]
	s_waitcnt lgkmcnt(2)
	v_mfma_f32_16x16x32_bf16 v[44:47], v[56:59], v[240:243], v[44:47]
	v_mul_f32_e64 v16, v16, v76
	v_mul_f32_e64 v17, v17, v76
	s_waitcnt lgkmcnt(0)
	s_barrier
	s_add_u32 s98, s100, s70
	s_addc_u32 s99, s101, s71
	s_add_u32 s98, s98, 0x70000
	s_addc_u32 s99, s99, 0
	s_lshl_b32 m0, s55, 10
	s_nop 0
	global_load_lds_dwordx4 v229, s[98:99]
	s_add_u32 m0, m0, 0x2000
	s_nop 0
	global_load_lds_dwordx4 v230, s[98:99]
	s_add_u32 m0, m0, 0x2000
	s_nop 0
	global_load_lds_dwordx4 v231, s[98:99]
	s_add_u32 m0, m0, 0x2000
	s_nop 0
	global_load_lds_dwordx4 v232, s[98:99]
	s_cmp_lg_u32 s55, 0
	s_cbranch_scc1 .Ldma_skip_loop
	s_mov_b32 m0, 0x8000
	s_nop 0
	global_load_lds_dwordx4 v233, s[98:99]
